# v68 + attention main loop: 12 of the 32 (s - rowmax) subtractions per KV step deferred from the MFMA-free middle into the PV-MFMA shadows (their max taken on raw scores, exact); x+0.0 adds dropped the
# baseline (speedup 1.0000x reference)
.LBB0_1604:
	v_add_u32_e32 v0, s22, v244
	ds_read_b64_tr_b16 v[208:209], v0 offset:24576
	ds_read_b64_tr_b16 v[210:211], v0 offset:25088
	s_waitcnt lgkmcnt(9)
	v_mfma_f32_32x32x16_bf16 v[112:127], v[204:207], v[172:175], 0
	v_add_f32_e32 v2, v87, v88
	v_cvt_pk_bf16_f32 v156, v96, v97
	v_cvt_pk_bf16_f32 v157, v98, v99
	ds_read_b64_tr_b16 v[204:205], v0 offset:28672
	ds_read_b64_tr_b16 v[206:207], v0 offset:29184
	v_add_f32_e32 v2, v89, v2
	v_cvt_pk_bf16_f32 v158, v100, v101
	v_cvt_pk_bf16_f32 v159, v102, v103
	s_waitcnt lgkmcnt(10)
	v_mfma_f32_32x32x16_bf16 v[128:143], v[200:203], v[172:175], 0
	ds_read_b64_tr_b16 v[10:11], v0 offset:25600
	ds_read_b64_tr_b16 v[12:13], v0 offset:26112
	s_waitcnt lgkmcnt(11)
	v_mfma_f32_32x32x16_bf16 v[112:127], v[196:199], v[168:171], v[112:127]
	v_add_f32_e32 v2, v90, v2
	v_cvt_pk_bf16_f32 v152, v104, v105
	v_cvt_pk_bf16_f32 v153, v106, v107
	ds_read_b64_tr_b16 v[6:7], v0 offset:29696
	ds_read_b64_tr_b16 v[8:9], v0 offset:30208
	v_add_f32_e32 v14, v91, v2
	v_cvt_pk_bf16_f32 v154, v108, v109
	v_cvt_pk_bf16_f32 v155, v110, v111
	s_waitcnt lgkmcnt(12)
	v_mfma_f32_32x32x16_bf16 v[128:143], v[192:195], v[168:171], v[128:143]
	ds_read_b64_tr_b16 v[2:3], v0 offset:26624
	ds_read_b64_tr_b16 v[4:5], v0 offset:27136
	s_waitcnt lgkmcnt(13)
	v_mfma_f32_32x32x16_bf16 v[112:127], v[188:191], v[164:167], v[112:127]
	v_add_f32_e32 v14, v92, v14
	v_cvt_pk_bf16_f32 v148, v80, v81
	v_cvt_pk_bf16_f32 v149, v82, v83
	ds_read_b64_tr_b16 v[196:197], v0 offset:30720
	ds_read_b64_tr_b16 v[198:199], v0 offset:31232
	v_add_f32_e32 v14, v93, v14
	v_cvt_pk_bf16_f32 v150, v84, v85
	v_cvt_pk_bf16_f32 v151, v86, v87
	s_waitcnt lgkmcnt(14)
	v_mfma_f32_32x32x16_bf16 v[128:143], v[184:187], v[164:167], v[128:143]
	ds_read_b64_tr_b16 v[192:193], v0 offset:27648
	ds_read_b64_tr_b16 v[194:195], v0 offset:28160
	s_waitcnt lgkmcnt(14)
	v_mfma_f32_32x32x16_bf16 v[112:127], v[180:183], v[160:163], v[112:127]
	v_add_f32_e32 v14, v94, v14
	v_cvt_pk_bf16_f32 v144, v88, v89
	v_cvt_pk_bf16_f32 v145, v90, v91
	ds_read_b64_tr_b16 v[188:189], v0 offset:31744
	ds_read_b64_tr_b16 v[190:191], v0 offset:32256
	v_add_f32_e32 v96, v95, v14
	v_cvt_pk_bf16_f32 v146, v92, v93
	v_cvt_pk_bf16_f32 v147, v94, v95
	v_mfma_f32_32x32x16_bf16 v[128:143], v[176:179], v[160:163], v[128:143]
	s_nop 2
	v_add_f32_e64 v80, v112, -v228
	v_add_f32_e64 v81, v113, -v228
	v_pk_add_f32 v[98:99], v[114:115], v[228:229] op_sel_hi:[1,0] neg_lo:[0,1] neg_hi:[0,1]
	v_pk_add_f32 v[100:101], v[116:117], v[228:229] op_sel_hi:[1,0] neg_lo:[0,1] neg_hi:[0,1]
	v_pk_add_f32 v[102:103], v[118:119], v[228:229] op_sel_hi:[1,0] neg_lo:[0,1] neg_hi:[0,1]
	v_pk_add_f32 v[104:105], v[120:121], v[228:229] op_sel_hi:[1,0] neg_lo:[0,1] neg_hi:[0,1]
	v_pk_add_f32 v[106:107], v[122:123], v[228:229] op_sel_hi:[1,0] neg_lo:[0,1] neg_hi:[0,1]
	v_pk_add_f32 v[108:109], v[124:125], v[228:229] op_sel_hi:[1,0] neg_lo:[0,1] neg_hi:[0,1]
	v_pk_add_f32 v[110:111], v[126:127], v[228:229] op_sel_hi:[1,0] neg_lo:[0,1] neg_hi:[0,1]
	v_max3_f32 v97, v80, v81, v98
	v_pk_add_f32 v[14:15], v[128:129], v[228:229] op_sel_hi:[1,0] neg_lo:[0,1] neg_hi:[0,1]
	v_max3_f32 v112, v99, v100, v101
	v_pk_add_f32 v[82:83], v[130:131], v[228:229] op_sel_hi:[1,0] neg_lo:[0,1] neg_hi:[0,1]
	v_max3_f32 v84, v132, v133, v134
	v_max3_f32 v97, v97, v102, v103
	s_add_u32 s30, s16, s10
	v_max3_f32 v84, v84, v135, v136
	s_addc_u32 s31, s17, s11
	v_max3_f32 v112, v112, v104, v105
	s_add_u32 s22, s30, 0x80000
	v_max3_f32 v84, v84, v137, v138
	s_addc_u32 s23, s31, 0
	v_max3_f32 v97, v97, v106, v107
	s_add_i32 s24, s29, s57
	v_max3_f32 v84, v84, v139, v140
	s_add_u32 s62, s18, s10
	v_max3_f32 v112, v112, v108, v109
	s_addc_u32 s63, s19, s11
	v_max3_f32 v84, v84, v141, v142
	v_max3_f32 v97, v97, v110, v111
	v_max_f32_e32 v84, v84, v143
	v_max3_f32 v112, v112, v14, v15
	v_sub_f32_e32 v84, v84, v228
	v_max3_f32 v97, v97, v82, v83
	s_mov_b32 s25, m0
	s_mov_b32 m0, s24
	s_nop 0
	global_load_lds_dwordx4 v241, s[22:23]
	s_mov_b32 m0, s25
	s_add_u32 s22, s62, 0x40000
	v_add_f32_e32 v116, v224, v96
	v_max3_f32 v96, v97, v84, v112
	s_addc_u32 s23, s63, 0
	s_add_i32 s24, s28, s58
	v_mov_b32_e32 v97, v96
	s_add_u32 s64, s20, s10
	s_nop 0
	v_permlane32_swap_b32_e32 v96, v97
	s_addc_u32 s65, s21, s11
	s_mov_b32 s25, m0
	s_mov_b32 m0, s24
	s_nop 0
	global_load_lds_dwordx4 v242, s[22:23]
	s_mov_b32 m0, s25
	s_add_u32 s22, s64, 0x40000
	v_max_f32_e32 v96, v96, v97
	s_addc_u32 s23, s65, 0
	s_add_i32 s24, s28, s59
	s_mov_b32 s25, m0
	s_mov_b32 m0, s24
	s_nop 0
	global_load_lds_dwordx4 v242, s[22:23]
	s_mov_b32 m0, s25
	v_cmp_lt_f32_e32 vcc, s35, v96
	s_cmp_lg_u64 vcc, 0
	s_cselect_b64 s[22:23], -1, 0
	s_cbranch_vccnz .LBB0_1612
.LBB0_1605:
	s_waitcnt lgkmcnt(14)
	v_mfma_f32_32x32x16_bf16 v[64:79], v[156:159], v[208:211], v[64:79]
	v_exp_f32_e32 v96, v80
	v_exp_f32_e32 v97, v81
	v_sub_f32_e32 v84, v132, v228
	v_sub_f32_e32 v85, v133, v228
	v_mov_b32_e32 v80, 0
	ds_read_b64_tr_b16 v[118:119], v0 offset:49152
	ds_read_b64_tr_b16 v[120:121], v0 offset:49664
	s_waitcnt lgkmcnt(14)
	v_mfma_f32_32x32x16_bf16 v[48:63], v[156:159], v[204:207], v[48:63]
	v_add_f32_e32 v80, v80, v96
	v_exp_f32_e32 v98, v98
	v_exp_f32_e32 v99, v99
	v_sub_f32_e32 v86, v134, v228
	v_sub_f32_e32 v87, v135, v228
	ds_read_b64_tr_b16 v[122:123], v0 offset:53248
	ds_read_b64_tr_b16 v[124:125], v0 offset:53760
	v_add_u32_e32 v81, s28, v243
	ds_read_b128 v[112:115], v81
	ds_read_b128 v[128:131], v81 offset:512
	s_waitcnt lgkmcnt(14)
	v_mfma_f32_32x32x16_bf16 v[64:79], v[152:155], v[10:13], v[64:79]
	v_add_f32_e32 v80, v80, v97
	v_exp_f32_e32 v100, v100
	v_exp_f32_e32 v101, v101
	v_sub_f32_e32 v88, v136, v228
	v_sub_f32_e32 v89, v137, v228
	ds_read_b64_tr_b16 v[132:133], v0 offset:50176
	ds_read_b64_tr_b16 v[134:135], v0 offset:50688
	ds_read_b128 v[184:187], v81 offset:2048
	ds_read_b128 v[176:179], v81 offset:2560
	v_mfma_f32_32x32x16_bf16 v[48:63], v[152:155], v[6:9], v[48:63]
	v_add_f32_e32 v10, v80, v98
	v_exp_f32_e32 v102, v102
	v_exp_f32_e32 v103, v103
	v_sub_f32_e32 v90, v138, v228
	v_sub_f32_e32 v91, v139, v228
	v_sub_f32_e32 v92, v140, v228
	v_sub_f32_e32 v93, v141, v228
	ds_read_b64_tr_b16 v[136:137], v0 offset:54272
	ds_read_b64_tr_b16 v[138:139], v0 offset:54784
	ds_read_b128 v[180:183], v81 offset:4096
	ds_read_b128 v[6:9], v81 offset:4608
	s_waitcnt lgkmcnt(14)
	v_mfma_f32_32x32x16_bf16 v[64:79], v[148:151], v[2:5], v[64:79]
	v_add_f32_e32 v10, v10, v99
	v_exp_f32_e32 v104, v104
	v_exp_f32_e32 v105, v105
	v_sub_f32_e32 v94, v142, v228
	v_sub_f32_e32 v95, v143, v228
	v_add_f32_e32 v80, 0, v10
	ds_read_b64_tr_b16 v[140:141], v0 offset:51200
	ds_read_b64_tr_b16 v[142:143], v0 offset:51712
	ds_read_b128 v[10:13], v81 offset:6144
	ds_read_b128 v[2:5], v81 offset:6656
	v_mfma_f32_32x32x16_bf16 v[48:63], v[148:151], v[196:199], v[48:63]
	v_add_f32_e32 v80, v80, v100
	v_exp_f32_e32 v106, v106
	v_exp_f32_e32 v107, v107
	ds_read_b64_tr_b16 v[196:197], v0 offset:55296
	ds_read_b64_tr_b16 v[198:199], v0 offset:55808
	v_mfma_f32_32x32x16_bf16 v[64:79], v[144:147], v[192:195], v[64:79]
	v_add_f32_e32 v80, v80, v101
	v_exp_f32_e32 v108, v108
	v_exp_f32_e32 v109, v109
	ds_read_b64_tr_b16 v[192:193], v0 offset:52224
	ds_read_b64_tr_b16 v[194:195], v0 offset:52736
	v_mfma_f32_32x32x16_bf16 v[48:63], v[144:147], v[188:191], v[48:63]
	v_add_f32_e32 v80, v80, v102
	v_exp_f32_e32 v110, v110
	v_exp_f32_e32 v111, v111
	v_add_f32_e32 v117, 0, v80
	ds_read_b64_tr_b16 v[188:189], v0 offset:56320
	ds_read_b64_tr_b16 v[190:191], v0 offset:56832
	s_waitcnt lgkmcnt(14)
	v_mfma_f32_32x32x16_bf16 v[32:47], v[156:159], v[118:121], v[32:47]
	v_add_f32_e32 v0, v117, v103
	v_exp_f32_e32 v80, v14
	v_exp_f32_e32 v81, v15
	v_add_f32_e32 v0, v104, v0
	v_mfma_f32_32x32x16_bf16 v[16:31], v[156:159], v[122:125], v[16:31]
	v_add_f32_e32 v0, v105, v0
	v_exp_f32_e32 v82, v82
	v_exp_f32_e32 v83, v83
	v_add_f32_e32 v0, v106, v0
	v_mfma_f32_32x32x16_bf16 v[32:47], v[152:155], v[132:135], v[32:47]
	v_add_f32_e32 v0, v107, v0
	v_exp_f32_e32 v84, v84
	v_exp_f32_e32 v85, v85
	v_add_f32_e32 v0, v108, v0
	s_waitcnt lgkmcnt(12)
	v_mfma_f32_32x32x16_bf16 v[16:31], v[152:155], v[136:139], v[16:31]
	v_add_f32_e32 v0, v109, v0
	v_exp_f32_e32 v86, v86
	v_exp_f32_e32 v87, v87
	v_add_f32_e32 v0, v110, v0
	s_waitcnt lgkmcnt(8)
	v_mfma_f32_32x32x16_bf16 v[32:47], v[148:151], v[140:143], v[32:47]
	v_add_f32_e32 v0, v111, v0
	v_exp_f32_e32 v88, v88
	v_exp_f32_e32 v89, v89
	v_add_f32_e32 v0, v0, v80
	s_waitcnt lgkmcnt(4)
	v_mfma_f32_32x32x16_bf16 v[16:31], v[148:151], v[196:199], v[16:31]
	v_add_f32_e32 v0, v0, v81
	v_exp_f32_e32 v90, v90
	v_exp_f32_e32 v91, v91
	v_add_f32_e32 v0, v82, v0
	s_waitcnt lgkmcnt(2)
	v_mfma_f32_32x32x16_bf16 v[32:47], v[144:147], v[192:195], v[32:47]
	v_add_f32_e32 v0, v0, v83
	v_exp_f32_e32 v92, v92
	v_exp_f32_e32 v93, v93
	v_add_f32_e32 v0, v84, v0
	s_waitcnt lgkmcnt(0)
	v_mfma_f32_32x32x16_bf16 v[16:31], v[144:147], v[188:191], v[16:31]
	v_add_f32_e32 v0, v0, v85
	v_exp_f32_e32 v94, v94
	v_exp_f32_e32 v95, v95
	v_add_f32_e32 v14, v86, v0
	s_waitcnt vmcnt(3) lgkmcnt(0)
	s_barrier
	s_andn2_b64 vcc, exec, s[22:23]
	v_add_u32_e32 v0, s56, v245
	s_cbranch_vccnz .LBB0_1607
	s_waitcnt lgkmcnt(0)
	ds_read_b128 v[118:121], v0 offset:96
	ds_read_b128 v[122:125], v0 offset:64
	ds_read_b128 v[132:135], v0 offset:32
	ds_read_b128 v[136:139], v0
	s_waitcnt lgkmcnt(3)
	v_pk_mul_f32 v[76:77], v[76:77], v[118:119]
	s_waitcnt lgkmcnt(2)
	v_pk_mul_f32 v[72:73], v[72:73], v[122:123]
	s_waitcnt lgkmcnt(1)
	v_pk_mul_f32 v[68:69], v[68:69], v[132:133]
	v_pk_mul_f32 v[78:79], v[78:79], v[120:121]
	v_pk_mul_f32 v[74:75], v[74:75], v[124:125]
	v_pk_mul_f32 v[70:71], v[70:71], v[134:135]
	s_waitcnt lgkmcnt(0)
	v_pk_mul_f32 v[66:67], v[66:67], v[138:139]
	v_pk_mul_f32 v[64:65], v[64:65], v[136:137]
	v_pk_mul_f32 v[60:61], v[60:61], v[118:119]
	v_pk_mul_f32 v[56:57], v[56:57], v[122:123]
	v_pk_mul_f32 v[52:53], v[52:53], v[132:133]
	v_pk_mul_f32 v[62:63], v[62:63], v[120:121]
	v_pk_mul_f32 v[58:59], v[58:59], v[124:125]
	v_pk_mul_f32 v[54:55], v[54:55], v[134:135]
	v_pk_mul_f32 v[50:51], v[50:51], v[138:139]
	v_pk_mul_f32 v[48:49], v[48:49], v[136:137]
	v_pk_mul_f32 v[44:45], v[44:45], v[118:119]
	v_pk_mul_f32 v[40:41], v[40:41], v[122:123]
	v_pk_mul_f32 v[36:37], v[36:37], v[132:133]
	v_pk_mul_f32 v[46:47], v[46:47], v[120:121]
	v_pk_mul_f32 v[42:43], v[42:43], v[124:125]
	v_pk_mul_f32 v[38:39], v[38:39], v[134:135]
	v_pk_mul_f32 v[34:35], v[34:35], v[138:139]
	v_pk_mul_f32 v[32:33], v[32:33], v[136:137]
	v_pk_mul_f32 v[28:29], v[28:29], v[118:119]
	v_pk_mul_f32 v[24:25], v[24:25], v[122:123]
	v_pk_mul_f32 v[20:21], v[20:21], v[132:133]
	v_pk_mul_f32 v[30:31], v[30:31], v[120:121]
	v_pk_mul_f32 v[26:27], v[26:27], v[124:125]
	v_pk_mul_f32 v[22:23], v[22:23], v[134:135]
	v_pk_mul_f32 v[18:19], v[18:19], v[138:139]
	v_pk_mul_f32 v[16:17], v[16:17], v[136:137]
.LBB0_1607:
	s_add_i32 s22, s28, 0x2000
	s_cmpk_lg_i32 s28, 0x4000
	s_cselect_b32 s61, s22, 0
	v_add_f32_e32 v15, v116, v14
	v_add_u32_e32 v14, s29, v244
	ds_read_b64_tr_b16 v[196:197], v14 offset:24576
	ds_read_b64_tr_b16 v[198:199], v14 offset:25088
	v_add_f32_e32 v132, v87, v88
	v_cvt_pk_bf16_f32 v156, v96, v97
	v_cvt_pk_bf16_f32 v157, v98, v99
	v_mfma_f32_32x32x16_bf16 v[112:127], v[112:115], v[172:175], 0
	ds_read_b64_tr_b16 v[192:193], v14 offset:28672
	ds_read_b64_tr_b16 v[194:195], v14 offset:29184
	v_add_f32_e32 v96, v89, v132
	v_cvt_pk_bf16_f32 v158, v100, v101
	v_cvt_pk_bf16_f32 v159, v102, v103
	v_mfma_f32_32x32x16_bf16 v[128:143], v[128:131], v[172:175], 0
	ds_read_b64_tr_b16 v[188:189], v14 offset:25600
	ds_read_b64_tr_b16 v[190:191], v14 offset:26112
	v_add_f32_e32 v96, v90, v96
	v_cvt_pk_bf16_f32 v152, v104, v105
	v_cvt_pk_bf16_f32 v153, v106, v107
	v_mfma_f32_32x32x16_bf16 v[112:127], v[184:187], v[168:171], v[112:127]
	ds_read_b64_tr_b16 v[184:185], v14 offset:29696
	ds_read_b64_tr_b16 v[186:187], v14 offset:30208
	v_add_f32_e32 v96, v91, v96
	v_cvt_pk_bf16_f32 v154, v108, v109
	v_cvt_pk_bf16_f32 v155, v110, v111
	v_mfma_f32_32x32x16_bf16 v[128:143], v[176:179], v[168:171], v[128:143]
	ds_read_b64_tr_b16 v[176:177], v14 offset:26624
	ds_read_b64_tr_b16 v[178:179], v14 offset:27136
	v_add_f32_e32 v96, v92, v96
	v_cvt_pk_bf16_f32 v148, v80, v81
	v_cvt_pk_bf16_f32 v149, v82, v83
	v_mfma_f32_32x32x16_bf16 v[112:127], v[180:183], v[164:167], v[112:127]
	ds_read_b64_tr_b16 v[212:213], v14 offset:30720
	ds_read_b64_tr_b16 v[214:215], v14 offset:31232
	v_add_f32_e32 v80, v93, v96
	v_cvt_pk_bf16_f32 v150, v84, v85
	v_cvt_pk_bf16_f32 v151, v86, v87
	v_mfma_f32_32x32x16_bf16 v[128:143], v[6:9], v[164:167], v[128:143]
	ds_read_b64_tr_b16 v[208:209], v14 offset:27648
	ds_read_b64_tr_b16 v[210:211], v14 offset:28160
	v_add_f32_e32 v80, v94, v80
	v_cvt_pk_bf16_f32 v144, v88, v89
	v_cvt_pk_bf16_f32 v145, v90, v91
	v_mfma_f32_32x32x16_bf16 v[112:127], v[10:13], v[160:163], v[112:127]
	ds_read_b64_tr_b16 v[6:7], v14 offset:31744
	ds_read_b64_tr_b16 v[8:9], v14 offset:32256
	v_add_f32_e32 v10, v95, v80
	v_cvt_pk_bf16_f32 v146, v92, v93
	v_cvt_pk_bf16_f32 v147, v94, v95
	v_mfma_f32_32x32x16_bf16 v[128:143], v[2:5], v[160:163], v[128:143]
	s_nop 5
	v_add_f32_e64 v4, v112, -v228
	v_add_f32_e64 v5, v113, -v228
	v_pk_add_f32 v[98:99], v[114:115], v[228:229] op_sel_hi:[1,0] neg_lo:[0,1] neg_hi:[0,1]
	v_pk_add_f32 v[100:101], v[116:117], v[228:229] op_sel_hi:[1,0] neg_lo:[0,1] neg_hi:[0,1]
	v_pk_add_f32 v[102:103], v[118:119], v[228:229] op_sel_hi:[1,0] neg_lo:[0,1] neg_hi:[0,1]
	v_pk_add_f32 v[104:105], v[120:121], v[228:229] op_sel_hi:[1,0] neg_lo:[0,1] neg_hi:[0,1]
	v_pk_add_f32 v[106:107], v[122:123], v[228:229] op_sel_hi:[1,0] neg_lo:[0,1] neg_hi:[0,1]
	v_pk_add_f32 v[108:109], v[124:125], v[228:229] op_sel_hi:[1,0] neg_lo:[0,1] neg_hi:[0,1]
	v_pk_add_f32 v[110:111], v[126:127], v[228:229] op_sel_hi:[1,0] neg_lo:[0,1] neg_hi:[0,1]
	v_max3_f32 v11, v4, v5, v98
	v_pk_add_f32 v[2:3], v[128:129], v[228:229] op_sel_hi:[1,0] neg_lo:[0,1] neg_hi:[0,1]
	v_max3_f32 v12, v99, v100, v101
	v_pk_add_f32 v[82:83], v[130:131], v[228:229] op_sel_hi:[1,0] neg_lo:[0,1] neg_hi:[0,1]
	v_max3_f32 v84, v132, v133, v134
	v_max3_f32 v11, v11, v102, v103
	s_add_u32 s22, s30, 0xa0000
	v_max3_f32 v84, v84, v135, v136
	v_max3_f32 v12, v12, v104, v105
	v_max3_f32 v84, v84, v137, v138
	v_max3_f32 v11, v11, v106, v107
	v_max3_f32 v84, v84, v139, v140
	v_max3_f32 v12, v12, v108, v109
	v_max3_f32 v84, v84, v141, v142
	v_max3_f32 v11, v11, v110, v111
	v_max_f32_e32 v84, v84, v143
	v_max3_f32 v12, v12, v2, v3
	v_sub_f32_e32 v84, v84, v228
	v_max3_f32 v11, v11, v82, v83
	v_max3_f32 v11, v11, v84, v12
	s_addc_u32 s23, s31, 0
	s_add_i32 s24, s28, s57
	v_mov_b32_e32 v12, v11
	s_mov_b32 s25, m0
	s_mov_b32 m0, s24
	s_nop 0
	global_load_lds_dwordx4 v241, s[22:23]
	s_mov_b32 m0, s25
	s_add_u32 s22, s62, 0x60000
	s_nop 0
	v_permlane32_swap_b32_e32 v11, v12
	s_addc_u32 s23, s63, 0
	s_add_i32 s24, s61, s58
	s_mov_b32 s25, m0
	s_mov_b32 m0, s24
	s_nop 0
	global_load_lds_dwordx4 v242, s[22:23]
	s_mov_b32 m0, s25
	s_add_u32 s22, s64, 0x60000
	v_max_f32_e32 v11, v11, v12
	s_addc_u32 s23, s65, 0
	s_add_i32 s24, s61, s59
	s_mov_b32 s25, m0
	s_mov_b32 m0, s24
	s_nop 0
	global_load_lds_dwordx4 v242, s[22:23]
	s_mov_b32 m0, s25
	v_cmp_lt_f32_e32 vcc, s35, v11
	s_cmp_lg_u64 vcc, 0
	v_add_f32_e32 v10, v15, v10
	s_cselect_b64 s[22:23], -1, 0
	s_cbranch_vccnz .LBB0_1615
.LBB0_1608:
	s_waitcnt lgkmcnt(14)
	v_mfma_f32_32x32x16_bf16 v[64:79], v[156:159], v[196:199], v[64:79]
	v_exp_f32_e32 v96, v4
	v_exp_f32_e32 v97, v5
	v_sub_f32_e32 v84, v132, v228
	v_sub_f32_e32 v85, v133, v228
	v_mov_b32_e32 v4, 0
	ds_read_b64_tr_b16 v[112:113], v14 offset:49152
	ds_read_b64_tr_b16 v[114:115], v14 offset:49664
	s_waitcnt lgkmcnt(14)
	v_mfma_f32_32x32x16_bf16 v[48:63], v[156:159], v[192:195], v[48:63]
	v_add_f32_e32 v4, v4, v96
	v_exp_f32_e32 v98, v98
	v_exp_f32_e32 v99, v99
	v_sub_f32_e32 v86, v134, v228
	v_sub_f32_e32 v87, v135, v228
	ds_read_b64_tr_b16 v[116:117], v14 offset:53248
	ds_read_b64_tr_b16 v[118:119], v14 offset:53760
	v_add_u32_e32 v5, s61, v243
	ds_read_b128 v[204:207], v5
	ds_read_b128 v[200:203], v5 offset:512
	s_waitcnt lgkmcnt(14)
	v_mfma_f32_32x32x16_bf16 v[64:79], v[152:155], v[188:191], v[64:79]
	v_add_f32_e32 v4, v4, v97
	v_exp_f32_e32 v100, v100
	v_exp_f32_e32 v101, v101
	v_sub_f32_e32 v88, v136, v228
	v_sub_f32_e32 v89, v137, v228
	ds_read_b64_tr_b16 v[120:121], v14 offset:50176
	ds_read_b64_tr_b16 v[122:123], v14 offset:50688
	ds_read_b128 v[196:199], v5 offset:2048
	ds_read_b128 v[192:195], v5 offset:2560
	v_mfma_f32_32x32x16_bf16 v[48:63], v[152:155], v[184:187], v[48:63]
	v_add_f32_e32 v4, v4, v98
	v_exp_f32_e32 v102, v102
	v_exp_f32_e32 v103, v103
	v_sub_f32_e32 v90, v138, v228
	v_sub_f32_e32 v91, v139, v228
	ds_read_b64_tr_b16 v[124:125], v14 offset:54272
	ds_read_b64_tr_b16 v[126:127], v14 offset:54784
	ds_read_b128 v[188:191], v5 offset:4096
	ds_read_b128 v[184:187], v5 offset:4608
	s_waitcnt lgkmcnt(14)
	v_mfma_f32_32x32x16_bf16 v[64:79], v[148:151], v[176:179], v[64:79]
	v_add_f32_e32 v4, v4, v99
	v_exp_f32_e32 v104, v104
	v_exp_f32_e32 v105, v105
	v_sub_f32_e32 v92, v140, v228
	v_sub_f32_e32 v93, v141, v228
	ds_read_b64_tr_b16 v[128:129], v14 offset:51200
	ds_read_b64_tr_b16 v[130:131], v14 offset:51712
	ds_read_b128 v[180:183], v5 offset:6144
	ds_read_b128 v[176:179], v5 offset:6656
	v_mfma_f32_32x32x16_bf16 v[48:63], v[148:151], v[212:215], v[48:63]
	v_add_f32_e32 v4, v4, v100
	v_exp_f32_e32 v106, v106
	v_exp_f32_e32 v107, v107
	v_sub_f32_e32 v94, v142, v228
	v_sub_f32_e32 v95, v143, v228
	ds_read_b64_tr_b16 v[132:133], v14 offset:55296
	ds_read_b64_tr_b16 v[134:135], v14 offset:55808
	v_mfma_f32_32x32x16_bf16 v[64:79], v[144:147], v[208:211], v[64:79]
	v_add_f32_e32 v4, v4, v101
	v_exp_f32_e32 v108, v108
	v_exp_f32_e32 v109, v109
	ds_read_b64_tr_b16 v[136:137], v14 offset:52224
	ds_read_b64_tr_b16 v[138:139], v14 offset:52736
	v_mfma_f32_32x32x16_bf16 v[48:63], v[144:147], v[6:9], v[48:63]
	v_add_f32_e32 v4, v4, v102
	v_exp_f32_e32 v110, v110
	v_exp_f32_e32 v111, v111
	v_add_f32_e32 v11, 0, v4
	ds_read_b64_tr_b16 v[4:5], v14 offset:56320
	ds_read_b64_tr_b16 v[6:7], v14 offset:56832
	s_waitcnt lgkmcnt(14)
	v_mfma_f32_32x32x16_bf16 v[32:47], v[156:159], v[112:115], v[32:47]
	v_exp_f32_e32 v80, v2
	v_add_f32_e32 v2, v11, v103
	v_exp_f32_e32 v81, v3
	v_add_f32_e32 v2, v104, v2
	v_mfma_f32_32x32x16_bf16 v[16:31], v[156:159], v[116:119], v[16:31]
	v_add_f32_e32 v2, v105, v2
	v_exp_f32_e32 v82, v82
	v_exp_f32_e32 v83, v83
	v_add_f32_e32 v2, v106, v2
	v_mfma_f32_32x32x16_bf16 v[32:47], v[152:155], v[120:123], v[32:47]
	v_add_f32_e32 v2, v107, v2
	v_exp_f32_e32 v84, v84
	v_exp_f32_e32 v85, v85
	v_add_f32_e32 v2, v108, v2
	s_waitcnt lgkmcnt(12)
	v_mfma_f32_32x32x16_bf16 v[16:31], v[152:155], v[124:127], v[16:31]
	v_add_f32_e32 v2, v109, v2
	v_exp_f32_e32 v86, v86
	v_exp_f32_e32 v87, v87
	v_add_f32_e32 v2, v110, v2
	s_waitcnt lgkmcnt(8)
	v_mfma_f32_32x32x16_bf16 v[32:47], v[148:151], v[128:131], v[32:47]
	v_add_f32_e32 v2, v111, v2
	v_exp_f32_e32 v88, v88
	v_exp_f32_e32 v89, v89
	v_add_f32_e32 v2, v2, v80
	s_waitcnt lgkmcnt(4)
	v_mfma_f32_32x32x16_bf16 v[16:31], v[148:151], v[132:135], v[16:31]
	v_add_f32_e32 v2, v2, v81
	v_exp_f32_e32 v90, v90
	v_exp_f32_e32 v91, v91
	v_add_f32_e32 v2, v82, v2
	s_waitcnt lgkmcnt(2)
	v_mfma_f32_32x32x16_bf16 v[32:47], v[144:147], v[136:139], v[32:47]
	v_add_f32_e32 v2, v2, v83
	v_exp_f32_e32 v92, v92
	v_exp_f32_e32 v93, v93
	v_add_f32_e32 v2, v84, v2
	s_waitcnt lgkmcnt(0)
	v_mfma_f32_32x32x16_bf16 v[16:31], v[144:147], v[4:7], v[16:31]
	v_add_f32_e32 v2, v2, v85
	v_exp_f32_e32 v94, v94
	v_exp_f32_e32 v95, v95
	v_add_f32_e32 v2, v86, v2
	s_waitcnt vmcnt(3) lgkmcnt(0)
	s_barrier
	s_andn2_b64 vcc, exec, s[22:23]
	s_cbranch_vccnz .LBB0_1610
	s_waitcnt lgkmcnt(0)
	ds_read_b128 v[4:7], v0 offset:96
	ds_read_b128 v[12:15], v0 offset:64
	ds_read_b128 v[112:115], v0 offset:32
	ds_read_b128 v[116:119], v0
	s_waitcnt lgkmcnt(3)
	v_pk_mul_f32 v[76:77], v[76:77], v[4:5]
	s_waitcnt lgkmcnt(2)
	v_pk_mul_f32 v[72:73], v[72:73], v[12:13]
	s_waitcnt lgkmcnt(1)
	v_pk_mul_f32 v[68:69], v[68:69], v[112:113]
	v_pk_mul_f32 v[78:79], v[78:79], v[6:7]
	v_pk_mul_f32 v[74:75], v[74:75], v[14:15]
	v_pk_mul_f32 v[70:71], v[70:71], v[114:115]
	s_waitcnt lgkmcnt(0)
	v_pk_mul_f32 v[66:67], v[66:67], v[118:119]
	v_pk_mul_f32 v[64:65], v[64:65], v[116:117]
	v_pk_mul_f32 v[60:61], v[60:61], v[4:5]
	v_pk_mul_f32 v[56:57], v[56:57], v[12:13]
	v_pk_mul_f32 v[52:53], v[52:53], v[112:113]
	v_pk_mul_f32 v[62:63], v[62:63], v[6:7]
	v_pk_mul_f32 v[58:59], v[58:59], v[14:15]
	v_pk_mul_f32 v[54:55], v[54:55], v[114:115]
	v_pk_mul_f32 v[50:51], v[50:51], v[118:119]
	v_pk_mul_f32 v[48:49], v[48:49], v[116:117]
	v_pk_mul_f32 v[44:45], v[44:45], v[4:5]
	v_pk_mul_f32 v[40:41], v[40:41], v[12:13]
	v_pk_mul_f32 v[36:37], v[36:37], v[112:113]
	v_pk_mul_f32 v[46:47], v[46:47], v[6:7]
	v_pk_mul_f32 v[42:43], v[42:43], v[14:15]
	v_pk_mul_f32 v[38:39], v[38:39], v[114:115]
	v_pk_mul_f32 v[34:35], v[34:35], v[118:119]
	v_pk_mul_f32 v[32:33], v[32:33], v[116:117]
	v_pk_mul_f32 v[28:29], v[28:29], v[4:5]
	v_pk_mul_f32 v[24:25], v[24:25], v[12:13]
	v_pk_mul_f32 v[20:21], v[20:21], v[112:113]
	v_pk_mul_f32 v[30:31], v[30:31], v[6:7]
	v_pk_mul_f32 v[26:27], v[26:27], v[14:15]
	v_pk_mul_f32 v[22:23], v[22:23], v[114:115]
	v_pk_mul_f32 v[18:19], v[18:19], v[118:119]
	v_pk_mul_f32 v[16:17], v[16:17], v[116:117]
